# hand-written NSA selected loop: 3 fragment sets, prefetch distance 2
# speedup vs baseline: 1.0092x; 1.0092x over previous
.LBB0_3923:
	s_lshl_b64 s[14:15], 1, s10
	s_or_b64 s[14:15], s[14:15], s[12:13]
	v_cmp_le_u64_e32 vcc, s[14:15], v[14:15]
	s_bcnt1_i32_b64 s16, vcc
	v_cmp_le_u64_e32 vcc, s[14:15], v[12:13]
	s_bcnt1_i32_b64 s17, vcc
	v_cmp_le_u64_e32 vcc, s[14:15], v[6:7]
	s_add_i32 s16, s17, s16
	s_bcnt1_i32_b64 s17, vcc
	v_cmp_le_u64_e32 vcc, s[14:15], v[4:5]
	s_add_i32 s16, s16, s17
	s_bcnt1_i32_b64 s17, vcc
	s_add_i32 s16, s16, s17
	s_cmp_gt_u32 s16, 15
	s_cselect_b32 s13, s15, s13
	s_cselect_b32 s12, s14, s12
	s_cmp_lg_u32 s16, 16
	s_cselect_b64 s[14:15], -1, 0
	s_cmp_lg_u32 s10, 0
	s_cselect_b64 s[16:17], -1, 0
	s_and_b64 s[14:15], s[14:15], s[16:17]
	s_add_u32 s10, s10, -1
	s_addc_u32 s11, s11, -1
	s_and_b64 vcc, exec, s[14:15]
	s_cbranch_vccnz .LBB0_3923
	v_cmp_le_u64_e32 vcc, s[12:13], v[14:15]
	s_nop 1
	v_and_b32_e32 v9, vcc_lo, v2
	v_and_b32_e32 v8, vcc_hi, v1
	v_bcnt_u32_b32 v9, v9, 0
	v_bcnt_u32_b32 v8, v8, v9
	v_mov_b32_e32 v9, v0
	v_cmp_gt_u64_e64 s[10:11], 16, v[8:9]
	s_and_b64 s[14:15], vcc, s[10:11]
	s_and_saveexec_b64 s[10:11], s[14:15]
	v_lshl_add_u32 v8, v8, 2, s61
	ds_write_b32 v8, v3
	s_or_b64 exec, exec, s[10:11]
	s_bcnt1_i32_b64 s14, vcc
	v_cmp_le_u64_e32 vcc, s[12:13], v[12:13]
	s_nop 1
	v_and_b32_e32 v8, vcc_lo, v2
	v_and_b32_e32 v3, vcc_hi, v1
	v_bcnt_u32_b32 v8, v8, 0
	v_bcnt_u32_b32 v3, v3, v8
	v_add_u32_e32 v3, s14, v3
	v_cmp_gt_u32_e64 s[10:11], 16, v3
	s_and_b64 s[16:17], vcc, s[10:11]
	s_and_saveexec_b64 s[10:11], s[16:17]
	v_lshl_add_u32 v3, v3, 2, s61
	ds_write_b32 v3, v11
	s_or_b64 exec, exec, s[10:11]
	s_bcnt1_i32_b64 s10, vcc
	v_cmp_le_u64_e32 vcc, s[12:13], v[6:7]
	s_add_i32 s14, s10, s14
	s_nop 0
	v_and_b32_e32 v6, vcc_lo, v2
	v_and_b32_e32 v3, vcc_hi, v1
	v_bcnt_u32_b32 v6, v6, 0
	v_bcnt_u32_b32 v3, v3, v6
	v_add_u32_e32 v3, s14, v3
	v_cmp_gt_u32_e64 s[10:11], 16, v3
	s_and_b64 s[16:17], vcc, s[10:11]
	s_and_saveexec_b64 s[10:11], s[16:17]
	v_lshl_add_u32 v3, v3, 2, s61
	ds_write_b32 v3, v20
	s_or_b64 exec, exec, s[10:11]
	s_bcnt1_i32_b64 s10, vcc
	v_cmp_le_u64_e32 vcc, s[12:13], v[4:5]
	s_add_i32 s14, s14, s10
	s_nop 0
	v_and_b32_e32 v2, vcc_lo, v2
	v_and_b32_e32 v1, vcc_hi, v1
	v_bcnt_u32_b32 v2, v2, 0
	v_bcnt_u32_b32 v1, v1, v2
	v_add_u32_e32 v1, s14, v1
	v_cmp_gt_u32_e64 s[10:11], 16, v1
	s_and_b64 s[12:13], vcc, s[10:11]
	s_and_saveexec_b64 s[10:11], s[12:13]
	v_lshl_add_u32 v1, v1, 2, s61
	ds_write_b32 v1, v21
	s_or_b64 exec, exec, s[10:11]
	v_cmp_gt_i32_e32 vcc, s6, v49
	v_mov_b32_e32 v1, s81
	v_mov_b32_e32 v2, s79
	v_cndmask_b32_e32 v3, v1, v2, vcc
	v_mov_b32_e32 v1, s80
	v_mov_b32_e32 v2, s78
	v_cndmask_b32_e32 v2, v1, v2, vcc
	v_and_b32_e32 v4, 0xff0, v124
	v_mov_b32_e32 v5, v0
	v_lshl_add_u64 v[6:7], v[2:3], 0, v[4:5]
	v_cndmask_b32_e64 v1, v174, 0, vcc
	v_mov_b32_e32 v2, s49
	s_movk_i32 s10, 0xfe
	v_add3_u32 v1, s6, v1, v4
	v_sub_u32_e64 v8, s10, v2 clamp
	global_load_dwordx4 v[2:5], v[6:7], off
	s_lshl_b32 s54, s48, 12
	s_mov_b32 s87, s55
	s_lshl_b64 s[12:13], s[86:87], 11
	s_add_u32 s10, s38, s12
	s_addc_u32 s11, s39, s13
	s_waitcnt vmcnt(0)
	ds_write_b128 v1, v[2:5]
	v_lshlrev_b32_e32 v2, 12, v8
	v_mov_b32_e32 v3, v0
	v_lshl_add_u64 v[2:3], v[6:7], 0, v[2:3]
	global_load_dwordx4 v[2:5], v[2:3], off
	s_waitcnt vmcnt(0)
	ds_write_b128 v1, v[2:5] offset:8192
	v_lshl_add_u64 v[2:3], v[6:7], 0, s[54:55]
	global_load_dwordx4 v[2:5], v[2:3], off
	v_mov_b32_e32 v7, v0
	s_waitcnt vmcnt(0)
	ds_write_b128 v1, v[2:5] offset:16384
	v_and_b32_e32 v4, 48, v49
	v_lshlrev_b32_e32 v2, 1, v121
	v_mov_b32_e32 v3, v0
	v_lshl_add_u64 v[2:3], s[10:11], 0, v[2:3]
	v_lshlrev_b32_e32 v6, 1, v4
	v_lshl_add_u64 v[6:7], v[2:3], 0, v[6:7]
	v_mov_b32_e32 v2, v0
	v_mov_b32_e32 v3, v0
	v_mov_b32_e32 v1, v0
	v_mov_b64_e32 v[72:73], v[2:3]
	v_cmp_gt_u32_e64 s[10:11], 4, v122
	v_mov_b64_e32 v[70:71], v[0:1]
	s_waitcnt lgkmcnt(0)
	s_barrier
	s_mov_b64 s[98:99], exec
	v_and_b32_e32 v1, 63, v160
	v_lshrrev_b32_e32 v147, 6, v160
	v_and_b32_e32 v193, 15, v1
	v_lshrrev_b32_e32 v187, 4, v1
	v_readfirstlane_b32 s22, v147
	v_mov_b32_e32 v157, 0
	v_lshlrev_b32_e32 v156, 6, v193
	v_lshl_or_b32 v156, v187, 4, v156
	v_lshl_add_u64 v[152:153], s[78:79], 0, v[156:157]
	v_lshl_add_u64 v[154:155], s[80:81], 0, v[156:157]
	v_add_u32_e32 v158, 0x100, v156
	v_xor_b32_e32 v190, 16, v1
	v_lshlrev_b32_e32 v190, 2, v190
	v_xor_b32_e32 v191, 32, v1
	v_lshlrev_b32_e32 v191, 2, v191
	v_cmp_gt_u32_e64 s[10:11], 4, v193
	v_mov_b32_e32 v192, 0xf149f2ca
	s_lshl_b32 s23, s22, 9
	s_add_i32 s23, s23, 0x20900
	v_lshl_add_u32 v147, v1, 2, s23
	ds_read_b32 v162, v147
	ds_read_b32 v163, v147 offset:256
	s_lshl_b32 s23, s22, 12
	s_add_i32 s23, s23, 0x8900
	v_lshl_add_u32 v164, v193, 7, s23
	v_lshl_add_u32 v164, v187, 3, v164
	s_lshl_b32 s21, s22, 3
	s_add_i32 s20, s48, -1
	s_lshl_b32 s25, s48, 6
	s_add_i32 s25, s25, s21
	s_and_b32 s54, s65, 3
	s_lshl_b32 s12, s25, 11
	s_lshl_b32 s23, s54, 9
	s_add_i32 s12, s12, s23
	s_add_u32 s12, s38, s12
	s_addc_u32 s13, s39, 0
	v_and_b32_e32 v156, 3, v193
	v_lshlrev_b32_e32 v156, 7, v156
	v_lshl_or_b32 v156, v187, 5, v156
	v_lshl_add_u64 v[166:167], s[12:13], 0, v[156:157]
	s_mul_i32 s12, s25, 0xc0
	s_lshl_b32 s23, s54, 4
	s_add_i32 s12, s12, s23
	s_add_i32 s12, s12, 0xf400040
	s_add_u32 s12, s38, s12
	s_addc_u32 s13, s39, 0
	v_lshlrev_b32_e32 v156, 2, v193
	v_lshl_add_u64 v[188:189], s[12:13], 0, v[156:157]
	v_lshlrev_b32_e32 v187, 2, v187
	s_mov_b32 s13, 0
	s_mov_b32 s101, 0
	v_mov_b32_e32 v136, 0
	v_mov_b32_e32 v137, 0
	v_mov_b32_e32 v138, 0
	v_mov_b32_e32 v139, 0
	v_mov_b32_e32 v140, 0
	v_mov_b32_e32 v141, 0
	v_mov_b32_e32 v142, 0
	v_mov_b32_e32 v143, 0
	s_mov_b64 exec, s[10:11]
	global_load_dwordx4 v[136:139], v[166:167], off
	global_load_dwordx4 v[140:143], v[166:167], off offset:16
	s_mov_b64 exec, s[98:99]
	s_waitcnt lgkmcnt(0)
	v_readlane_b32 s15, v162, 0
	v_readlane_b32 s16, v162, 1
	s_mov_b32 s18, 0
	s_cmp_lt_i32 s15, 0
	s_cbranch_scc1 .Lsel_fd_2
	s_mov_b32 s23, 0
	s_cmp_eq_u32 s15, 0
	s_cbranch_scc1 .Lsel_fl_3
	s_movk_i32 s23, 0x4000
	s_cmp_eq_u32 s15, s48
	s_cbranch_scc1 .Lsel_fl_3
	s_movk_i32 s23, 0x2000
	s_cmp_eq_u32 s15, s20
	s_cbranch_scc1 .Lsel_fl_3
	s_lshl_b32 s12, s15, 12
	s_mov_b32 s18, 1
	v_lshl_add_u64 v[156:157], v[152:153], 0, s[12:13]
	global_load_dwordx4 v[2:5], v[156:157], off
	global_load_dwordx4 v[6:9], v[156:157], off offset:1024
	global_load_dwordx4 v[10:13], v[156:157], off offset:2048
	global_load_dwordx4 v[14:17], v[156:157], off offset:3072
	v_lshl_add_u64 v[156:157], v[154:155], 0, s[12:13]
	global_load_dwordx4 v[18:21], v[156:157], off
	global_load_dwordx4 v[22:25], v[156:157], off offset:1024
	global_load_dwordx4 v[26:29], v[156:157], off offset:2048
	global_load_dwordx4 v[30:33], v[156:157], off offset:3072
	s_branch .Lsel_fd_2
.Lsel_fl_3:
	v_add_u32_e32 v159, s23, v158
	ds_read_b128 v[2:5], v159
	ds_read_b128 v[6:9], v159 offset:1024
	ds_read_b128 v[10:13], v159 offset:2048
	ds_read_b128 v[14:17], v159 offset:3072
	ds_read_b128 v[18:21], v159 offset:4096
	ds_read_b128 v[22:25], v159 offset:5120
	ds_read_b128 v[26:29], v159 offset:6144
	ds_read_b128 v[30:33], v159 offset:7168
	s_waitcnt lgkmcnt(0)
.Lsel_fd_2:
	s_mov_b32 s54, s18
	s_mov_b32 s18, 0
	s_cmp_lt_i32 s16, 0
	s_cbranch_scc1 .Lsel_fd_5
	s_mov_b32 s23, 0
	s_cmp_eq_u32 s16, 0
	s_cbranch_scc1 .Lsel_fl_6
	s_movk_i32 s23, 0x4000
	s_cmp_eq_u32 s16, s48
	s_cbranch_scc1 .Lsel_fl_6
	s_movk_i32 s23, 0x2000
	s_cmp_eq_u32 s16, s20
	s_cbranch_scc1 .Lsel_fl_6
	s_lshl_b32 s12, s16, 12
	s_mov_b32 s18, 1
	v_lshl_add_u64 v[156:157], v[152:153], 0, s[12:13]
	global_load_dwordx4 v[34:37], v[156:157], off
	global_load_dwordx4 v[38:41], v[156:157], off offset:1024
	global_load_dwordx4 v[42:45], v[156:157], off offset:2048
	global_load_dwordx4 v[46:49], v[156:157], off offset:3072
	v_lshl_add_u64 v[156:157], v[154:155], 0, s[12:13]
	global_load_dwordx4 v[50:53], v[156:157], off
	global_load_dwordx4 v[54:57], v[156:157], off offset:1024
	global_load_dwordx4 v[58:61], v[156:157], off offset:2048
	global_load_dwordx4 v[62:65], v[156:157], off offset:3072
	s_branch .Lsel_fd_5
.Lsel_fl_6:
	v_add_u32_e32 v159, s23, v158
	ds_read_b128 v[34:37], v159
	ds_read_b128 v[38:41], v159 offset:1024
	ds_read_b128 v[42:45], v159 offset:2048
	ds_read_b128 v[46:49], v159 offset:3072
	ds_read_b128 v[50:53], v159 offset:4096
	ds_read_b128 v[54:57], v159 offset:5120
	ds_read_b128 v[58:61], v159 offset:6144
	ds_read_b128 v[62:65], v159 offset:7168
	s_waitcnt lgkmcnt(0)
.Lsel_fd_5:
	s_add_i32 s22, s54, s18
	s_cmp_eq_u32 s22, 2
	s_cbranch_scc1 .Lsel_w16_8
	s_cmp_eq_u32 s22, 1
	s_cbranch_scc1 .Lsel_w8_7
	s_waitcnt vmcnt(0)
	s_branch .Lsel_wd_9
.Lsel_w8_7:
	s_waitcnt vmcnt(8)
	s_branch .Lsel_wd_9
.Lsel_w16_8:
	s_waitcnt vmcnt(16)
.Lsel_wd_9:
	s_mov_b32 s14, 0
.Lsel_step0:
	s_and_b32 s54, s14, 15
	s_cmp_lg_u32 s54, 0
	s_cbranch_scc1 .Lsel_in_10
	v_lshlrev_b32_e32 v244, 16, v136
	v_and_b32_e32 v245, 0xffff0000, v136
	v_mul_f32_e32 v244, 0x40b17218, v244
	v_mul_f32_e32 v245, 0x40b17218, v245
	v_cvt_pk_fp8_f32 v118, v244, v245
	v_lshlrev_b32_e32 v246, 16, v137
	v_and_b32_e32 v247, 0xffff0000, v137
	v_mul_f32_e32 v246, 0x40b17218, v246
	v_mul_f32_e32 v247, 0x40b17218, v247
	v_cvt_pk_fp8_f32 v118, v246, v247 op_sel:[0,0,1]
	v_lshlrev_b32_e32 v244, 16, v138
	v_and_b32_e32 v245, 0xffff0000, v138
	v_mul_f32_e32 v244, 0x40b17218, v244
	v_mul_f32_e32 v245, 0x40b17218, v245
	v_cvt_pk_fp8_f32 v119, v244, v245
	v_lshlrev_b32_e32 v246, 16, v139
	v_and_b32_e32 v247, 0xffff0000, v139
	v_mul_f32_e32 v246, 0x40b17218, v246
	v_mul_f32_e32 v247, 0x40b17218, v247
	v_cvt_pk_fp8_f32 v119, v246, v247 op_sel:[0,0,1]
	v_lshlrev_b32_e32 v244, 16, v140
	v_and_b32_e32 v245, 0xffff0000, v140
	v_mul_f32_e32 v244, 0x40b17218, v244
	v_mul_f32_e32 v245, 0x40b17218, v245
	v_cvt_pk_fp8_f32 v120, v244, v245
	v_lshlrev_b32_e32 v246, 16, v141
	v_and_b32_e32 v247, 0xffff0000, v141
	v_mul_f32_e32 v246, 0x40b17218, v246
	v_mul_f32_e32 v247, 0x40b17218, v247
	v_cvt_pk_fp8_f32 v120, v246, v247 op_sel:[0,0,1]
	v_lshlrev_b32_e32 v244, 16, v142
	v_and_b32_e32 v245, 0xffff0000, v142
	v_mul_f32_e32 v244, 0x40b17218, v244
	v_mul_f32_e32 v245, 0x40b17218, v245
	v_cvt_pk_fp8_f32 v121, v244, v245
	v_lshlrev_b32_e32 v246, 16, v143
	v_and_b32_e32 v247, 0xffff0000, v143
	v_mul_f32_e32 v246, 0x40b17218, v246
	v_mul_f32_e32 v247, 0x40b17218, v247
	v_cvt_pk_fp8_f32 v121, v246, v247 op_sel:[0,0,1]
	v_mov_b32_e32 v144, v192
	v_mov_b32_e32 v145, 0
	v_mov_b32_e32 v102, 0
	v_mov_b32_e32 v103, 0
	v_mov_b32_e32 v104, 0
	v_mov_b32_e32 v105, 0
	v_mov_b32_e32 v106, 0
	v_mov_b32_e32 v107, 0
	v_mov_b32_e32 v108, 0
	v_mov_b32_e32 v109, 0
	v_mov_b32_e32 v110, 0
	v_mov_b32_e32 v111, 0
	v_mov_b32_e32 v112, 0
	v_mov_b32_e32 v113, 0
	v_mov_b32_e32 v114, 0
	v_mov_b32_e32 v115, 0
	v_mov_b32_e32 v116, 0
	v_mov_b32_e32 v117, 0
	s_mov_b64 exec, s[10:11]
	global_load_dword v150, v[188:189], off
	s_cmp_ge_u32 s14, 0x70
	s_cbranch_scc1 .Lsel_nq_14
	s_mov_b32 s100, 0x800
	v_lshl_add_u64 v[166:167], v[166:167], 0, s[100:101]
	global_load_dwordx4 v[136:139], v[166:167], off
	global_load_dwordx4 v[140:143], v[166:167], off offset:16
.Lsel_nq_14:
	s_mov_b64 exec, s[98:99]
	s_movk_i32 s100, 0xc0
	v_lshl_add_u64 v[188:189], v[188:189], 0, s[100:101]
.Lsel_in_10:
	s_add_i32 s25, s14, 2
	s_cmp_ge_u32 s25, 0x80
	s_cbranch_scc1 .Lsel_rn_17
	s_and_b32 s23, s25, 63
	s_cmp_ge_u32 s25, 64
	s_cbranch_scc1 .Lsel_rh_15
	v_readlane_b32 s17, v162, s23
	s_branch .Lsel_rd_16
.Lsel_rh_15:
	v_readlane_b32 s17, v163, s23
	s_branch .Lsel_rd_16
.Lsel_rn_17:
	s_mov_b32 s17, -1
.Lsel_rd_16:
	s_mov_b32 s19, 0
	s_cmp_lt_i32 s17, 0
	s_cbranch_scc1 .Lsel_fd_19
	s_mov_b32 s23, 0
	s_cmp_eq_u32 s17, 0
	s_cbranch_scc1 .Lsel_fl_20
	s_movk_i32 s23, 0x4000
	s_cmp_eq_u32 s17, s48
	s_cbranch_scc1 .Lsel_fl_20
	s_movk_i32 s23, 0x2000
	s_cmp_eq_u32 s17, s20
	s_cbranch_scc1 .Lsel_fl_20
	s_lshl_b32 s12, s17, 12
	s_mov_b32 s19, 1
	v_lshl_add_u64 v[156:157], v[152:153], 0, s[12:13]
	global_load_dwordx4 v[212:215], v[156:157], off
	global_load_dwordx4 v[216:219], v[156:157], off offset:1024
	global_load_dwordx4 v[220:223], v[156:157], off offset:2048
	global_load_dwordx4 v[224:227], v[156:157], off offset:3072
	v_lshl_add_u64 v[156:157], v[154:155], 0, s[12:13]
	global_load_dwordx4 v[228:231], v[156:157], off
	global_load_dwordx4 v[232:235], v[156:157], off offset:1024
	global_load_dwordx4 v[236:239], v[156:157], off offset:2048
	global_load_dwordx4 v[240:243], v[156:157], off offset:3072
	s_branch .Lsel_fd_19
.Lsel_fl_20:
	v_add_u32_e32 v159, s23, v158
	ds_read_b128 v[212:215], v159
	ds_read_b128 v[216:219], v159 offset:1024
	ds_read_b128 v[220:223], v159 offset:2048
	ds_read_b128 v[224:227], v159 offset:3072
	ds_read_b128 v[228:231], v159 offset:4096
	ds_read_b128 v[232:235], v159 offset:5120
	ds_read_b128 v[236:239], v159 offset:6144
	ds_read_b128 v[240:243], v159 offset:7168
	s_waitcnt lgkmcnt(0)
.Lsel_fd_19:
	s_cmp_lt_i32 s15, 0
	s_cbranch_scc1 .Lsel_sk_12
	s_add_i32 s22, s18, s19
	s_cmp_eq_u32 s22, 2
	s_cbranch_scc1 .Lsel_w16_22
	s_cmp_eq_u32 s22, 1
	s_cbranch_scc1 .Lsel_w8_21
	s_waitcnt vmcnt(0)
	s_branch .Lsel_wd_23

.Lsel_wd_23:
	s_cmp_eq_u32 s15, s48
	s_cselect_b32 s24, s21, 63
	s_setprio 1
	v_mfma_f32_16x16x32_fp8_fp8 v[66:69], v[2:3], v[118:119], 0
	v_mfma_f32_16x16x32_fp8_fp8 v[70:73], v[6:7], v[118:119], 0
	v_mfma_f32_16x16x32_fp8_fp8 v[74:77], v[10:11], v[118:119], 0
	v_mfma_f32_16x16x32_fp8_fp8 v[78:81], v[14:15], v[118:119], 0
	v_mfma_f32_16x16x32_fp8_fp8 v[66:69], v[4:5], v[120:121], v[66:69]
	v_mfma_f32_16x16x32_fp8_fp8 v[70:73], v[8:9], v[120:121], v[70:73]
	v_mfma_f32_16x16x32_fp8_fp8 v[74:77], v[12:13], v[120:121], v[74:77]
	v_mfma_f32_16x16x32_fp8_fp8 v[78:81], v[16:17], v[120:121], v[78:81]
	s_setprio 0
	s_cmp_gt_i32 s24, 62
	s_nop 7
	s_cbranch_scc1 .Lsel_nm_24
	v_sub_u32_e32 v244, s24, v187
	v_cmp_gt_i32_e64 s[22:23], 0, v244
	v_cmp_gt_i32_e64 s[100:101], 1, v244
	v_cmp_gt_i32_e64 s[12:13], 2, v244
	v_cmp_gt_i32_e32 vcc, 3, v244
	v_cndmask_b32_e64 v66, v66, v192, s[22:23]
	v_cndmask_b32_e64 v67, v67, v192, s[100:101]
	v_cndmask_b32_e64 v68, v68, v192, s[12:13]
	v_cndmask_b32_e32 v69, v69, v192, vcc
	v_sub_u32_e32 v244, s24, v187
	v_subrev_u32_e32 v244, 16, v244
	v_cmp_gt_i32_e64 s[22:23], 0, v244
	v_cmp_gt_i32_e64 s[100:101], 1, v244
	v_cmp_gt_i32_e64 s[12:13], 2, v244
	v_cmp_gt_i32_e32 vcc, 3, v244
	v_cndmask_b32_e64 v70, v70, v192, s[22:23]
	v_cndmask_b32_e64 v71, v71, v192, s[100:101]
	v_cndmask_b32_e64 v72, v72, v192, s[12:13]
	v_cndmask_b32_e32 v73, v73, v192, vcc
	v_sub_u32_e32 v244, s24, v187
	v_subrev_u32_e32 v244, 32, v244
	v_cmp_gt_i32_e64 s[22:23], 0, v244
	v_cmp_gt_i32_e64 s[100:101], 1, v244
	v_cmp_gt_i32_e64 s[12:13], 2, v244
	v_cmp_gt_i32_e32 vcc, 3, v244
	v_cndmask_b32_e64 v74, v74, v192, s[22:23]
	v_cndmask_b32_e64 v75, v75, v192, s[100:101]
	v_cndmask_b32_e64 v76, v76, v192, s[12:13]
	v_cndmask_b32_e32 v77, v77, v192, vcc
	v_sub_u32_e32 v244, s24, v187
	v_subrev_u32_e32 v244, 48, v244
	v_cmp_gt_i32_e64 s[22:23], 0, v244
	v_cmp_gt_i32_e64 s[100:101], 1, v244
	v_cmp_gt_i32_e64 s[12:13], 2, v244
	v_cmp_gt_i32_e32 vcc, 3, v244
	v_cndmask_b32_e64 v78, v78, v192, s[22:23]
	v_cndmask_b32_e64 v79, v79, v192, s[100:101]
	v_cndmask_b32_e64 v80, v80, v192, s[12:13]
	v_cndmask_b32_e32 v81, v81, v192, vcc
	s_mov_b32 s13, 0
	s_mov_b32 s101, 0
.Lsel_nm_24:
	v_max3_f32 v146, v66, v67, v68
	v_max3_f32 v147, v69, v70, v71
	v_max3_f32 v146, v146, v72, v73
	v_max3_f32 v147, v147, v74, v75
	v_max3_f32 v146, v146, v76, v77
	v_max3_f32 v147, v147, v78, v79
	v_max3_f32 v146, v146, v80, v81
	v_max_f32_e32 v146, v146, v147
	v_mul_f32_e32 v146, 0x3e38aa3b, v146
	v_add_f32_e32 v147, 0x41000000, v144
	v_cmp_gt_f32_e32 vcc, v146, v147
	s_cbranch_vccz .Lsel_nr_25
	ds_bpermute_b32 v147, v190, v146
	s_waitcnt lgkmcnt(0)
	v_max_f32_e32 v147, v146, v147
	ds_bpermute_b32 v148, v191, v147
	s_waitcnt lgkmcnt(0)
	v_max_f32_e32 v147, v147, v148
	v_max_f32_e32 v147, v144, v147
	v_sub_f32_e32 v148, v144, v147
	v_exp_f32_e32 v148, v148
	v_mov_b32_e32 v144, v147
	s_nop 0
	v_mul_f32_e32 v145, v145, v148
	v_mul_f32_e32 v102, v102, v148
	v_mul_f32_e32 v103, v103, v148
	v_mul_f32_e32 v104, v104, v148
	v_mul_f32_e32 v105, v105, v148
	v_mul_f32_e32 v106, v106, v148
	v_mul_f32_e32 v107, v107, v148
	v_mul_f32_e32 v108, v108, v148
	v_mul_f32_e32 v109, v109, v148
	v_mul_f32_e32 v110, v110, v148
	v_mul_f32_e32 v111, v111, v148
	v_mul_f32_e32 v112, v112, v148
	v_mul_f32_e32 v113, v113, v148
	v_mul_f32_e32 v114, v114, v148
	v_mul_f32_e32 v115, v115, v148
	v_mul_f32_e32 v116, v116, v148
	v_mul_f32_e32 v117, v117, v148
.Lsel_nr_25:
	s_mov_b32 s25, 0x3e38aa3b
	v_fma_f32 v66, v66, s25, -v144
	v_fma_f32 v67, v67, s25, -v144
	v_fma_f32 v68, v68, s25, -v144
	v_fma_f32 v69, v69, s25, -v144
	v_fma_f32 v70, v70, s25, -v144
	v_fma_f32 v71, v71, s25, -v144
	v_fma_f32 v72, v72, s25, -v144
	v_fma_f32 v73, v73, s25, -v144
	v_fma_f32 v74, v74, s25, -v144
	v_fma_f32 v75, v75, s25, -v144
	v_fma_f32 v76, v76, s25, -v144
	v_fma_f32 v77, v77, s25, -v144
	v_fma_f32 v78, v78, s25, -v144
	v_fma_f32 v79, v79, s25, -v144
	v_fma_f32 v80, v80, s25, -v144
	v_fma_f32 v81, v81, s25, -v144
	v_exp_f32_e32 v66, v66
	v_exp_f32_e32 v67, v67
	v_exp_f32_e32 v68, v68
	v_exp_f32_e32 v69, v69
	v_exp_f32_e32 v70, v70
	v_exp_f32_e32 v71, v71
	v_exp_f32_e32 v72, v72
	v_exp_f32_e32 v73, v73
	v_exp_f32_e32 v74, v74
	v_exp_f32_e32 v75, v75
	v_exp_f32_e32 v76, v76
	v_exp_f32_e32 v77, v77
	v_exp_f32_e32 v78, v78
	v_exp_f32_e32 v79, v79
	v_exp_f32_e32 v80, v80
	v_exp_f32_e32 v81, v81
	v_add_f32_e32 v244, v66, v70
	v_add_f32_e32 v245, v67, v71
	v_add_f32_e32 v246, v68, v72
	v_add_f32_e32 v247, v69, v73
	v_add_f32_e32 v248, v74, v78
	v_add_f32_e32 v249, v75, v79
	v_add_f32_e32 v250, v76, v80
	v_add_f32_e32 v251, v77, v81
	v_add_f32_e32 v244, v244, v248
	v_add_f32_e32 v245, v245, v249
	v_add_f32_e32 v246, v246, v250
	v_add_f32_e32 v247, v247, v251
	v_cvt_pk_fp8_f32 v122, v66, v67
	v_cvt_pk_fp8_f32 v123, v70, v71
	v_cvt_pk_fp8_f32 v124, v74, v75
	v_cvt_pk_fp8_f32 v125, v78, v79
	v_add_f32_e32 v244, v244, v245
	v_cvt_pk_fp8_f32 v122, v68, v69 op_sel:[0,0,1]
	v_cvt_pk_fp8_f32 v123, v72, v73 op_sel:[0,0,1]
	v_cvt_pk_fp8_f32 v124, v76, v77 op_sel:[0,0,1]
	v_cvt_pk_fp8_f32 v125, v80, v81 op_sel:[0,0,1]
	v_add_f32_e32 v246, v246, v247
	v_add_f32_e32 v244, v244, v246
	v_add_f32_e32 v145, v145, v244
	s_setprio 1
	v_mfma_f32_16x16x32_fp8_fp8 v[102:105], v[18:19], v[122:123], v[102:105]
	v_mfma_f32_16x16x32_fp8_fp8 v[106:109], v[22:23], v[122:123], v[106:109]
	v_mfma_f32_16x16x32_fp8_fp8 v[110:113], v[26:27], v[122:123], v[110:113]
	v_mfma_f32_16x16x32_fp8_fp8 v[114:117], v[30:31], v[122:123], v[114:117]
	v_mfma_f32_16x16x32_fp8_fp8 v[102:105], v[20:21], v[124:125], v[102:105]
	v_mfma_f32_16x16x32_fp8_fp8 v[106:109], v[24:25], v[124:125], v[106:109]
	v_mfma_f32_16x16x32_fp8_fp8 v[110:113], v[28:29], v[124:125], v[110:113]
	v_mfma_f32_16x16x32_fp8_fp8 v[114:117], v[32:33], v[124:125], v[114:117]
	s_setprio 0
.Lsel_sk_12:
	s_and_b32 s54, s14, 15
	s_cmp_lg_u32 s54, 15
	s_cbranch_scc1 .Lsel_fi_11
	ds_bpermute_b32 v147, v190, v145
	s_waitcnt lgkmcnt(0)
	v_add_f32_e32 v145, v145, v147
	ds_bpermute_b32 v147, v191, v145
	s_waitcnt lgkmcnt(0)
	v_add_f32_e32 v145, v145, v147
	s_add_i32 s22, s18, s19
	s_cmp_eq_u32 s22, 2
	s_cbranch_scc1 .Lsel_w16_27
	s_cmp_eq_u32 s22, 1
	s_cbranch_scc1 .Lsel_w8_26
	s_waitcnt vmcnt(0)
	s_branch .Lsel_wd_28

.Lsel_wd_28:
	s_mov_b64 exec, s[10:11]
	v_div_scale_f32 v244, s[22:23], v145, v145, v150
	v_rcp_f32_e32 v245, v244
	s_nop 0
	v_fma_f32 v246, -v244, v245, 1.0
	v_fmac_f32_e32 v245, v246, v245
	v_div_scale_f32 v246, vcc, v150, v145, v150
	v_mul_f32_e32 v247, v246, v245
	v_fma_f32 v248, -v244, v247, v246
	v_fmac_f32_e32 v247, v248, v245
	v_fma_f32 v244, -v244, v247, v246
	v_div_fmas_f32 v244, v244, v245, v247
	v_div_fixup_f32 v252, v244, v145, v150
	ds_read2_b64 v[244:247], v164 offset0:0 offset1:4
	s_waitcnt lgkmcnt(0)
	v_lshlrev_b32_e32 v248, 16, v244
	v_and_b32_e32 v249, 0xffff0000, v244
	v_lshlrev_b32_e32 v250, 16, v245
	v_and_b32_e32 v251, 0xffff0000, v245
	v_fma_f32 v248, v102, v252, v248
	v_fma_f32 v249, v103, v252, v249
	v_fma_f32 v250, v104, v252, v250
	v_fma_f32 v251, v105, v252, v251
	v_cvt_pk_bf16_f32 v244, v248, v249
	v_cvt_pk_bf16_f32 v245, v250, v251
	v_lshlrev_b32_e32 v248, 16, v246
	v_and_b32_e32 v249, 0xffff0000, v246
	v_lshlrev_b32_e32 v250, 16, v247
	v_and_b32_e32 v251, 0xffff0000, v247
	v_fma_f32 v248, v106, v252, v248
	v_fma_f32 v249, v107, v252, v249
	v_fma_f32 v250, v108, v252, v250
	v_fma_f32 v251, v109, v252, v251
	v_cvt_pk_bf16_f32 v246, v248, v249
	v_cvt_pk_bf16_f32 v247, v250, v251
	ds_write2_b64 v164, v[244:245], v[246:247] offset0:0 offset1:4
	ds_read2_b64 v[244:247], v164 offset0:8 offset1:12
	s_waitcnt lgkmcnt(0)
	v_lshlrev_b32_e32 v248, 16, v244
	v_and_b32_e32 v249, 0xffff0000, v244
	v_lshlrev_b32_e32 v250, 16, v245
	v_and_b32_e32 v251, 0xffff0000, v245
	v_fma_f32 v248, v110, v252, v248
	v_fma_f32 v249, v111, v252, v249
	v_fma_f32 v250, v112, v252, v250
	v_fma_f32 v251, v113, v252, v251
	v_cvt_pk_bf16_f32 v244, v248, v249
	v_cvt_pk_bf16_f32 v245, v250, v251
	v_lshlrev_b32_e32 v248, 16, v246
	v_and_b32_e32 v249, 0xffff0000, v246
	v_lshlrev_b32_e32 v250, 16, v247
	v_and_b32_e32 v251, 0xffff0000, v247
	v_fma_f32 v248, v114, v252, v248
	v_fma_f32 v249, v115, v252, v249
	v_fma_f32 v250, v116, v252, v250
	v_fma_f32 v251, v117, v252, v251
	v_cvt_pk_bf16_f32 v246, v248, v249
	v_cvt_pk_bf16_f32 v247, v250, v251
	ds_write2_b64 v164, v[244:245], v[246:247] offset0:8 offset1:12
	s_mov_b64 exec, s[98:99]
	v_add_u32_e32 v164, 0x200, v164
	s_add_i32 s21, s21, 1
.Lsel_fi_11:
	s_mov_b32 s15, s16
	s_mov_b32 s16, s17
	s_mov_b32 s18, s19
	s_add_i32 s14, s14, 1
	s_cmpk_eq_i32 s14, 0x80
	s_cbranch_scc1 .Lsel_exit

.Lsel_rd_35:
	s_mov_b32 s19, 0
	s_cmp_lt_i32 s17, 0
	s_cbranch_scc1 .Lsel_fd_38
	s_mov_b32 s23, 0
	s_cmp_eq_u32 s17, 0
	s_cbranch_scc1 .Lsel_fl_39
	s_movk_i32 s23, 0x4000
	s_cmp_eq_u32 s17, s48
	s_cbranch_scc1 .Lsel_fl_39
	s_movk_i32 s23, 0x2000
	s_cmp_eq_u32 s17, s20
	s_cbranch_scc1 .Lsel_fl_39
	s_lshl_b32 s12, s17, 12
	s_mov_b32 s19, 1
	v_lshl_add_u64 v[156:157], v[152:153], 0, s[12:13]
	global_load_dwordx4 v[2:5], v[156:157], off
	global_load_dwordx4 v[6:9], v[156:157], off offset:1024
	global_load_dwordx4 v[10:13], v[156:157], off offset:2048
	global_load_dwordx4 v[14:17], v[156:157], off offset:3072
	v_lshl_add_u64 v[156:157], v[154:155], 0, s[12:13]
	global_load_dwordx4 v[18:21], v[156:157], off
	global_load_dwordx4 v[22:25], v[156:157], off offset:1024
	global_load_dwordx4 v[26:29], v[156:157], off offset:2048
	global_load_dwordx4 v[30:33], v[156:157], off offset:3072
	s_branch .Lsel_fd_38

.Lsel_wd_42:
	s_cmp_eq_u32 s15, s48
	s_cselect_b32 s24, s21, 63
	s_setprio 1
	v_mfma_f32_16x16x32_fp8_fp8 v[66:69], v[34:35], v[118:119], 0
	v_mfma_f32_16x16x32_fp8_fp8 v[70:73], v[38:39], v[118:119], 0
	v_mfma_f32_16x16x32_fp8_fp8 v[74:77], v[42:43], v[118:119], 0
	v_mfma_f32_16x16x32_fp8_fp8 v[78:81], v[46:47], v[118:119], 0
	v_mfma_f32_16x16x32_fp8_fp8 v[66:69], v[36:37], v[120:121], v[66:69]
	v_mfma_f32_16x16x32_fp8_fp8 v[70:73], v[40:41], v[120:121], v[70:73]
	v_mfma_f32_16x16x32_fp8_fp8 v[74:77], v[44:45], v[120:121], v[74:77]
	v_mfma_f32_16x16x32_fp8_fp8 v[78:81], v[48:49], v[120:121], v[78:81]
	s_setprio 0
	s_cmp_gt_i32 s24, 62
	s_nop 7
	s_cbranch_scc1 .Lsel_nm_43
	v_sub_u32_e32 v244, s24, v187
	v_cmp_gt_i32_e64 s[22:23], 0, v244
	v_cmp_gt_i32_e64 s[100:101], 1, v244
	v_cmp_gt_i32_e64 s[12:13], 2, v244
	v_cmp_gt_i32_e32 vcc, 3, v244
	v_cndmask_b32_e64 v66, v66, v192, s[22:23]
	v_cndmask_b32_e64 v67, v67, v192, s[100:101]
	v_cndmask_b32_e64 v68, v68, v192, s[12:13]
	v_cndmask_b32_e32 v69, v69, v192, vcc
	v_sub_u32_e32 v244, s24, v187
	v_subrev_u32_e32 v244, 16, v244
	v_cmp_gt_i32_e64 s[22:23], 0, v244
	v_cmp_gt_i32_e64 s[100:101], 1, v244
	v_cmp_gt_i32_e64 s[12:13], 2, v244
	v_cmp_gt_i32_e32 vcc, 3, v244
	v_cndmask_b32_e64 v70, v70, v192, s[22:23]
	v_cndmask_b32_e64 v71, v71, v192, s[100:101]
	v_cndmask_b32_e64 v72, v72, v192, s[12:13]
	v_cndmask_b32_e32 v73, v73, v192, vcc
	v_sub_u32_e32 v244, s24, v187
	v_subrev_u32_e32 v244, 32, v244
	v_cmp_gt_i32_e64 s[22:23], 0, v244
	v_cmp_gt_i32_e64 s[100:101], 1, v244
	v_cmp_gt_i32_e64 s[12:13], 2, v244
	v_cmp_gt_i32_e32 vcc, 3, v244
	v_cndmask_b32_e64 v74, v74, v192, s[22:23]
	v_cndmask_b32_e64 v75, v75, v192, s[100:101]
	v_cndmask_b32_e64 v76, v76, v192, s[12:13]
	v_cndmask_b32_e32 v77, v77, v192, vcc
	v_sub_u32_e32 v244, s24, v187
	v_subrev_u32_e32 v244, 48, v244
	v_cmp_gt_i32_e64 s[22:23], 0, v244
	v_cmp_gt_i32_e64 s[100:101], 1, v244
	v_cmp_gt_i32_e64 s[12:13], 2, v244
	v_cmp_gt_i32_e32 vcc, 3, v244
	v_cndmask_b32_e64 v78, v78, v192, s[22:23]
	v_cndmask_b32_e64 v79, v79, v192, s[100:101]
	v_cndmask_b32_e64 v80, v80, v192, s[12:13]
	v_cndmask_b32_e32 v81, v81, v192, vcc
	s_mov_b32 s13, 0
	s_mov_b32 s101, 0

.Lsel_nr_44:
	s_mov_b32 s25, 0x3e38aa3b
	v_fma_f32 v66, v66, s25, -v144
	v_fma_f32 v67, v67, s25, -v144
	v_fma_f32 v68, v68, s25, -v144
	v_fma_f32 v69, v69, s25, -v144
	v_fma_f32 v70, v70, s25, -v144
	v_fma_f32 v71, v71, s25, -v144
	v_fma_f32 v72, v72, s25, -v144
	v_fma_f32 v73, v73, s25, -v144
	v_fma_f32 v74, v74, s25, -v144
	v_fma_f32 v75, v75, s25, -v144
	v_fma_f32 v76, v76, s25, -v144
	v_fma_f32 v77, v77, s25, -v144
	v_fma_f32 v78, v78, s25, -v144
	v_fma_f32 v79, v79, s25, -v144
	v_fma_f32 v80, v80, s25, -v144
	v_fma_f32 v81, v81, s25, -v144
	v_exp_f32_e32 v66, v66
	v_exp_f32_e32 v67, v67
	v_exp_f32_e32 v68, v68
	v_exp_f32_e32 v69, v69
	v_exp_f32_e32 v70, v70
	v_exp_f32_e32 v71, v71
	v_exp_f32_e32 v72, v72
	v_exp_f32_e32 v73, v73
	v_exp_f32_e32 v74, v74
	v_exp_f32_e32 v75, v75
	v_exp_f32_e32 v76, v76
	v_exp_f32_e32 v77, v77
	v_exp_f32_e32 v78, v78
	v_exp_f32_e32 v79, v79
	v_exp_f32_e32 v80, v80
	v_exp_f32_e32 v81, v81
	v_add_f32_e32 v244, v66, v70
	v_add_f32_e32 v245, v67, v71
	v_add_f32_e32 v246, v68, v72
	v_add_f32_e32 v247, v69, v73
	v_add_f32_e32 v248, v74, v78
	v_add_f32_e32 v249, v75, v79
	v_add_f32_e32 v250, v76, v80
	v_add_f32_e32 v251, v77, v81
	v_add_f32_e32 v244, v244, v248
	v_add_f32_e32 v245, v245, v249
	v_add_f32_e32 v246, v246, v250
	v_add_f32_e32 v247, v247, v251
	v_cvt_pk_fp8_f32 v122, v66, v67
	v_cvt_pk_fp8_f32 v123, v70, v71
	v_cvt_pk_fp8_f32 v124, v74, v75
	v_cvt_pk_fp8_f32 v125, v78, v79
	v_add_f32_e32 v244, v244, v245
	v_cvt_pk_fp8_f32 v122, v68, v69 op_sel:[0,0,1]
	v_cvt_pk_fp8_f32 v123, v72, v73 op_sel:[0,0,1]
	v_cvt_pk_fp8_f32 v124, v76, v77 op_sel:[0,0,1]
	v_cvt_pk_fp8_f32 v125, v80, v81 op_sel:[0,0,1]
	v_add_f32_e32 v246, v246, v247
	v_add_f32_e32 v244, v244, v246
	v_add_f32_e32 v145, v145, v244
	s_setprio 1
	v_mfma_f32_16x16x32_fp8_fp8 v[102:105], v[50:51], v[122:123], v[102:105]
	v_mfma_f32_16x16x32_fp8_fp8 v[106:109], v[54:55], v[122:123], v[106:109]
	v_mfma_f32_16x16x32_fp8_fp8 v[110:113], v[58:59], v[122:123], v[110:113]
	v_mfma_f32_16x16x32_fp8_fp8 v[114:117], v[62:63], v[122:123], v[114:117]
	v_mfma_f32_16x16x32_fp8_fp8 v[102:105], v[52:53], v[124:125], v[102:105]
	v_mfma_f32_16x16x32_fp8_fp8 v[106:109], v[56:57], v[124:125], v[106:109]
	v_mfma_f32_16x16x32_fp8_fp8 v[110:113], v[60:61], v[124:125], v[110:113]
	v_mfma_f32_16x16x32_fp8_fp8 v[114:117], v[64:65], v[124:125], v[114:117]
	s_setprio 0

.Lsel_rd_54:
	s_mov_b32 s19, 0
	s_cmp_lt_i32 s17, 0
	s_cbranch_scc1 .Lsel_fd_57
	s_mov_b32 s23, 0
	s_cmp_eq_u32 s17, 0
	s_cbranch_scc1 .Lsel_fl_58
	s_movk_i32 s23, 0x4000
	s_cmp_eq_u32 s17, s48
	s_cbranch_scc1 .Lsel_fl_58
	s_movk_i32 s23, 0x2000
	s_cmp_eq_u32 s17, s20
	s_cbranch_scc1 .Lsel_fl_58
	s_lshl_b32 s12, s17, 12
	s_mov_b32 s19, 1
	v_lshl_add_u64 v[156:157], v[152:153], 0, s[12:13]
	global_load_dwordx4 v[34:37], v[156:157], off
	global_load_dwordx4 v[38:41], v[156:157], off offset:1024
	global_load_dwordx4 v[42:45], v[156:157], off offset:2048
	global_load_dwordx4 v[46:49], v[156:157], off offset:3072
	v_lshl_add_u64 v[156:157], v[154:155], 0, s[12:13]
	global_load_dwordx4 v[50:53], v[156:157], off
	global_load_dwordx4 v[54:57], v[156:157], off offset:1024
	global_load_dwordx4 v[58:61], v[156:157], off offset:2048
	global_load_dwordx4 v[62:65], v[156:157], off offset:3072
	s_branch .Lsel_fd_57

.Lsel_wd_61:
	s_cmp_eq_u32 s15, s48
	s_cselect_b32 s24, s21, 63
	s_setprio 1
	v_mfma_f32_16x16x32_fp8_fp8 v[66:69], v[212:213], v[118:119], 0
	v_mfma_f32_16x16x32_fp8_fp8 v[70:73], v[216:217], v[118:119], 0
	v_mfma_f32_16x16x32_fp8_fp8 v[74:77], v[220:221], v[118:119], 0
	v_mfma_f32_16x16x32_fp8_fp8 v[78:81], v[224:225], v[118:119], 0
	v_mfma_f32_16x16x32_fp8_fp8 v[66:69], v[214:215], v[120:121], v[66:69]
	v_mfma_f32_16x16x32_fp8_fp8 v[70:73], v[218:219], v[120:121], v[70:73]
	v_mfma_f32_16x16x32_fp8_fp8 v[74:77], v[222:223], v[120:121], v[74:77]
	v_mfma_f32_16x16x32_fp8_fp8 v[78:81], v[226:227], v[120:121], v[78:81]
	s_setprio 0
	s_cmp_gt_i32 s24, 62
	s_nop 7
	s_cbranch_scc1 .Lsel_nm_62
	v_sub_u32_e32 v244, s24, v187
	v_cmp_gt_i32_e64 s[22:23], 0, v244
	v_cmp_gt_i32_e64 s[100:101], 1, v244
	v_cmp_gt_i32_e64 s[12:13], 2, v244
	v_cmp_gt_i32_e32 vcc, 3, v244
	v_cndmask_b32_e64 v66, v66, v192, s[22:23]
	v_cndmask_b32_e64 v67, v67, v192, s[100:101]
	v_cndmask_b32_e64 v68, v68, v192, s[12:13]
	v_cndmask_b32_e32 v69, v69, v192, vcc
	v_sub_u32_e32 v244, s24, v187
	v_subrev_u32_e32 v244, 16, v244
	v_cmp_gt_i32_e64 s[22:23], 0, v244
	v_cmp_gt_i32_e64 s[100:101], 1, v244
	v_cmp_gt_i32_e64 s[12:13], 2, v244
	v_cmp_gt_i32_e32 vcc, 3, v244
	v_cndmask_b32_e64 v70, v70, v192, s[22:23]
	v_cndmask_b32_e64 v71, v71, v192, s[100:101]
	v_cndmask_b32_e64 v72, v72, v192, s[12:13]
	v_cndmask_b32_e32 v73, v73, v192, vcc
	v_sub_u32_e32 v244, s24, v187
	v_subrev_u32_e32 v244, 32, v244
	v_cmp_gt_i32_e64 s[22:23], 0, v244
	v_cmp_gt_i32_e64 s[100:101], 1, v244
	v_cmp_gt_i32_e64 s[12:13], 2, v244
	v_cmp_gt_i32_e32 vcc, 3, v244
	v_cndmask_b32_e64 v74, v74, v192, s[22:23]
	v_cndmask_b32_e64 v75, v75, v192, s[100:101]
	v_cndmask_b32_e64 v76, v76, v192, s[12:13]
	v_cndmask_b32_e32 v77, v77, v192, vcc
	v_sub_u32_e32 v244, s24, v187
	v_subrev_u32_e32 v244, 48, v244
	v_cmp_gt_i32_e64 s[22:23], 0, v244
	v_cmp_gt_i32_e64 s[100:101], 1, v244
	v_cmp_gt_i32_e64 s[12:13], 2, v244
	v_cmp_gt_i32_e32 vcc, 3, v244
	v_cndmask_b32_e64 v78, v78, v192, s[22:23]
	v_cndmask_b32_e64 v79, v79, v192, s[100:101]
	v_cndmask_b32_e64 v80, v80, v192, s[12:13]
	v_cndmask_b32_e32 v81, v81, v192, vcc
	s_mov_b32 s13, 0
	s_mov_b32 s101, 0

.Lsel_nr_63:
	s_mov_b32 s25, 0x3e38aa3b
	v_fma_f32 v66, v66, s25, -v144
	v_fma_f32 v67, v67, s25, -v144
	v_fma_f32 v68, v68, s25, -v144
	v_fma_f32 v69, v69, s25, -v144
	v_fma_f32 v70, v70, s25, -v144
	v_fma_f32 v71, v71, s25, -v144
	v_fma_f32 v72, v72, s25, -v144
	v_fma_f32 v73, v73, s25, -v144
	v_fma_f32 v74, v74, s25, -v144
	v_fma_f32 v75, v75, s25, -v144
	v_fma_f32 v76, v76, s25, -v144
	v_fma_f32 v77, v77, s25, -v144
	v_fma_f32 v78, v78, s25, -v144
	v_fma_f32 v79, v79, s25, -v144
	v_fma_f32 v80, v80, s25, -v144
	v_fma_f32 v81, v81, s25, -v144
	v_exp_f32_e32 v66, v66
	v_exp_f32_e32 v67, v67
	v_exp_f32_e32 v68, v68
	v_exp_f32_e32 v69, v69
	v_exp_f32_e32 v70, v70
	v_exp_f32_e32 v71, v71
	v_exp_f32_e32 v72, v72
	v_exp_f32_e32 v73, v73
	v_exp_f32_e32 v74, v74
	v_exp_f32_e32 v75, v75
	v_exp_f32_e32 v76, v76
	v_exp_f32_e32 v77, v77
	v_exp_f32_e32 v78, v78
	v_exp_f32_e32 v79, v79
	v_exp_f32_e32 v80, v80
	v_exp_f32_e32 v81, v81
	v_add_f32_e32 v244, v66, v70
	v_add_f32_e32 v245, v67, v71
	v_add_f32_e32 v246, v68, v72
	v_add_f32_e32 v247, v69, v73
	v_add_f32_e32 v248, v74, v78
	v_add_f32_e32 v249, v75, v79
	v_add_f32_e32 v250, v76, v80
	v_add_f32_e32 v251, v77, v81
	v_add_f32_e32 v244, v244, v248
	v_add_f32_e32 v245, v245, v249
	v_add_f32_e32 v246, v246, v250
	v_add_f32_e32 v247, v247, v251
	v_cvt_pk_fp8_f32 v122, v66, v67
	v_cvt_pk_fp8_f32 v123, v70, v71
	v_cvt_pk_fp8_f32 v124, v74, v75
	v_cvt_pk_fp8_f32 v125, v78, v79
	v_add_f32_e32 v244, v244, v245
	v_cvt_pk_fp8_f32 v122, v68, v69 op_sel:[0,0,1]
	v_cvt_pk_fp8_f32 v123, v72, v73 op_sel:[0,0,1]
	v_cvt_pk_fp8_f32 v124, v76, v77 op_sel:[0,0,1]
	v_cvt_pk_fp8_f32 v125, v80, v81 op_sel:[0,0,1]
	v_add_f32_e32 v246, v246, v247
	v_add_f32_e32 v244, v244, v246
	v_add_f32_e32 v145, v145, v244
	s_setprio 1
	v_mfma_f32_16x16x32_fp8_fp8 v[102:105], v[228:229], v[122:123], v[102:105]
	v_mfma_f32_16x16x32_fp8_fp8 v[106:109], v[232:233], v[122:123], v[106:109]
	v_mfma_f32_16x16x32_fp8_fp8 v[110:113], v[236:237], v[122:123], v[110:113]
	v_mfma_f32_16x16x32_fp8_fp8 v[114:117], v[240:241], v[122:123], v[114:117]
	v_mfma_f32_16x16x32_fp8_fp8 v[102:105], v[230:231], v[124:125], v[102:105]
	v_mfma_f32_16x16x32_fp8_fp8 v[106:109], v[234:235], v[124:125], v[106:109]
	v_mfma_f32_16x16x32_fp8_fp8 v[110:113], v[238:239], v[124:125], v[110:113]
	v_mfma_f32_16x16x32_fp8_fp8 v[114:117], v[242:243], v[124:125], v[114:117]
	s_setprio 0

.Lsel_fi_49:
	s_mov_b32 s15, s16
	s_mov_b32 s16, s17
	s_mov_b32 s18, s19
	s_add_i32 s14, s14, 1
	s_cmpk_eq_i32 s14, 0x80
	s_cbranch_scc1 .Lsel_exit
	s_branch .Lsel_step0
.Lsel_exit:
	s_mov_b64 exec, s[98:99]

	.amdhsa_kernel _Z8mega_fwd4Args
		.amdhsa_group_segment_fixed_size 256
		.amdhsa_private_segment_fixed_size 0
		.amdhsa_kernarg_size 560
		.amdhsa_user_sgpr_count 2
		.amdhsa_user_sgpr_dispatch_ptr 0
		.amdhsa_user_sgpr_queue_ptr 0
		.amdhsa_user_sgpr_kernarg_segment_ptr 1
		.amdhsa_user_sgpr_dispatch_id 0
		.amdhsa_user_sgpr_kernarg_preload_length 0
		.amdhsa_user_sgpr_kernarg_preload_offset 0
		.amdhsa_user_sgpr_private_segment_size 0
		.amdhsa_uses_dynamic_stack 0
		.amdhsa_enable_private_segment 0
		.amdhsa_system_sgpr_workgroup_id_x 1
		.amdhsa_system_sgpr_workgroup_id_y 0
		.amdhsa_system_sgpr_workgroup_id_z 0
		.amdhsa_system_sgpr_workgroup_info 0
		.amdhsa_system_vgpr_workitem_id 2
		.amdhsa_next_free_vgpr 255
		.amdhsa_next_free_sgpr 102
		.amdhsa_accum_offset 256
		.amdhsa_reserve_vcc 1
		.amdhsa_float_round_mode_32 0
		.amdhsa_float_round_mode_16_64 0
		.amdhsa_float_denorm_mode_32 3
		.amdhsa_float_denorm_mode_16_64 3
		.amdhsa_dx10_clamp 1
		.amdhsa_ieee_mode 1
		.amdhsa_fp16_overflow 0
		.amdhsa_tg_split 0
		.amdhsa_exception_fp_ieee_invalid_op 0
		.amdhsa_exception_fp_denorm_src 0
		.amdhsa_exception_fp_ieee_div_zero 0
		.amdhsa_exception_fp_ieee_overflow 0
		.amdhsa_exception_fp_ieee_underflow 0
		.amdhsa_exception_fp_ieee_inexact 0
		.amdhsa_exception_int_div_zero 0
	.end_amdhsa_kernel

amdhsa.kernels:
  - .agpr_count:     0
    .args:
      - .offset:         0
        .size:           304
        .value_kind:     by_value
      - .offset:         304
        .size:           4
        .value_kind:     hidden_block_count_x
      - .offset:         308
        .size:           4
        .value_kind:     hidden_block_count_y
      - .offset:         312
        .size:           4
        .value_kind:     hidden_block_count_z
      - .offset:         316
        .size:           2
        .value_kind:     hidden_group_size_x
      - .offset:         318
        .size:           2
        .value_kind:     hidden_group_size_y
      - .offset:         320
        .size:           2
        .value_kind:     hidden_group_size_z
      - .offset:         322
        .size:           2
        .value_kind:     hidden_remainder_x
      - .offset:         324
        .size:           2
        .value_kind:     hidden_remainder_y
      - .offset:         326
        .size:           2
        .value_kind:     hidden_remainder_z
      - .offset:         344
        .size:           8
        .value_kind:     hidden_global_offset_x
      - .offset:         352
        .size:           8
        .value_kind:     hidden_global_offset_y
      - .offset:         360
        .size:           8
        .value_kind:     hidden_global_offset_z
      - .offset:         368
        .size:           2
        .value_kind:     hidden_grid_dims
      - .offset:         392
        .size:           8
        .value_kind:     hidden_multigrid_sync_arg
      - .offset:         424
        .size:           4
        .value_kind:     hidden_dynamic_lds_size
    .group_segment_fixed_size: 256
    .kernarg_segment_align: 8
    .kernarg_segment_size: 560
    .language:       OpenCL C
    .language_version:
      - 2
      - 0
    .max_flat_workgroup_size: 512
    .name:           _Z8mega_fwd4Args
    .private_segment_fixed_size: 0
    .sgpr_count:     108
    .sgpr_spill_count: 48
    .symbol:         _Z8mega_fwd4Args.kd
    .uniform_work_group_size: 1
    .uses_dynamic_stack: false
    .vgpr_count:     255
    .vgpr_spill_count: 0
    .wavefront_size: 64
